# attention: fused scale+bias fma, batched K reads at QK head; pool W=16/8 rows branch-free (zero halo makes masks redundant); attention item rebalance; phase13-14 barrier dropped
# speedup vs baseline: 1.0156x; 1.0099x over previous
.LBB0_162:
	v_add_u32_e32 v102, s15, v231
	ds_read_b128 v[22:25], v102
	ds_read_b128 v[26:29], v102 offset:32
	ds_read_b128 v[240:243], v102 offset:64
	ds_read_b128 v[244:247], v102 offset:96
	ds_read_b128 v[248:251], v102 offset:128
	ds_read_b128 v[130:133], v102 offset:160
	ds_read_b128 v[134:137], v102 offset:192
	ds_read_b128 v[104:107], v102 offset:224
	s_mul_i32 s14, s9, 0x5000
	s_addk_i32 s14, 0x3800
	s_cmp_lg_u32 s9, 0
	s_cselect_b32 s9, s14, 0x12800
	v_add_u32_e32 v233, s9, v232
	s_lshr_b32 s9, s5, 8
	v_lshrrev_b32_e32 v234, s9, v217
	v_and_b32_e32 v234, 1, v234
	v_cmp_eq_u32_e32 vcc, 1, v234
	s_add_i32 s5, s5, 64
	s_cmp_lg_u32 s4, s8
	v_cndmask_b32_e32 v234, v16, v14, vcc
	v_cndmask_b32_e64 v234, v234, v32, s[6:7]
	s_waitcnt lgkmcnt(7)
	v_mfma_f32_32x32x16_bf16 v[114:129], v[22:25], v[162:165], 0
	ds_read_b128 v[98:101], v102 offset:8704
	s_waitcnt lgkmcnt(7)
	v_mfma_f32_32x32x16_bf16 v[114:129], v[26:29], v[166:169], v[114:129]
	ds_read_b128 v[158:161], v102 offset:8736
	s_waitcnt lgkmcnt(7)
	v_mfma_f32_32x32x16_bf16 v[114:129], v[240:243], v[170:173], v[114:129]
	ds_read_b128 v[236:239], v102 offset:8768
	s_waitcnt lgkmcnt(7)
	v_mfma_f32_32x32x16_bf16 v[114:129], v[244:247], v[174:177], v[114:129]
	ds_read_b128 v[154:157], v102 offset:8800
	s_waitcnt lgkmcnt(7)
	v_mfma_f32_32x32x16_bf16 v[114:129], v[248:251], v[178:181], v[114:129]
	ds_read_b128 v[150:153], v102 offset:8832
	s_waitcnt lgkmcnt(7)
	v_mfma_f32_32x32x16_bf16 v[114:129], v[130:133], v[182:185], v[114:129]
	ds_read_b128 v[146:149], v102 offset:8864
	s_waitcnt lgkmcnt(7)
	v_mfma_f32_32x32x16_bf16 v[114:129], v[134:137], v[186:189], v[114:129]
	ds_read_b128 v[142:145], v102 offset:8896
	s_waitcnt lgkmcnt(7)
	v_mfma_f32_32x32x16_bf16 v[114:129], v[104:107], v[190:193], v[114:129]
	ds_read_b128 v[138:141], v102 offset:8928
	s_waitcnt lgkmcnt(7)
	v_mfma_f32_32x32x16_bf16 v[98:113], v[98:101], v[162:165], 0
	s_waitcnt lgkmcnt(6)
	v_mfma_f32_32x32x16_bf16 v[98:113], v[158:161], v[166:169], v[98:113]
	s_waitcnt lgkmcnt(5)
	v_mfma_f32_32x32x16_bf16 v[98:113], v[236:239], v[170:173], v[98:113]
	s_waitcnt lgkmcnt(4)
	v_mfma_f32_32x32x16_bf16 v[98:113], v[154:157], v[174:177], v[98:113]
	s_waitcnt lgkmcnt(3)
	v_mfma_f32_32x32x16_bf16 v[98:113], v[150:153], v[178:181], v[98:113]
	s_waitcnt lgkmcnt(2)
	v_mfma_f32_32x32x16_bf16 v[98:113], v[146:149], v[182:185], v[98:113]
	s_waitcnt lgkmcnt(1)
	v_mfma_f32_32x32x16_bf16 v[98:113], v[142:145], v[186:189], v[98:113]
	ds_read_b64_tr_b16 v[134:135], v233
	ds_read_b64_tr_b16 v[26:27], v233 offset:64
	ds_read_b64_tr_b16 v[130:131], v233 offset:128
	ds_read_b64_tr_b16 v[22:23], v233 offset:192
	ds_read_b64_tr_b16 v[136:137], v233 offset:2560
	ds_read_b64_tr_b16 v[28:29], v233 offset:2624
	ds_read_b64_tr_b16 v[132:133], v233 offset:2688
	ds_read_b128 v[240:243], v15
	ds_read_b128 v[248:251], v15 offset:32
	ds_read_b128 v[236:239], v15 offset:64
	ds_read_b128 v[154:157], v15 offset:96
	ds_read_b64_tr_b16 v[24:25], v233 offset:2752
	ds_read_b64_tr_b16 v[150:151], v233 offset:5120
	s_waitcnt lgkmcnt(13)
	v_mfma_f32_32x32x16_bf16 v[98:113], v[138:141], v[190:193], v[98:113]
	ds_read_b128 v[244:247], v15 offset:128
	ds_read_b128 v[158:161], v15 offset:160
	s_waitcnt lgkmcnt(7)
	s_waitcnt lgkmcnt(6)
	v_mfma_f32_32x32x16_bf16 v[34:49], v[134:137], v[18:21], v[34:49]
	s_waitcnt lgkmcnt(5)
	s_waitcnt lgkmcnt(4)
	v_fma_f32 v240, v114, s66, -v240
	v_fma_f32 v241, v115, s66, -v241
	v_fma_f32 v242, v116, s66, -v242
	v_fma_f32 v243, v117, s66, -v243
	v_fma_f32 v248, v118, s66, -v248
	v_fma_f32 v249, v119, s66, -v249
	v_fma_f32 v250, v120, s66, -v250
	v_fma_f32 v251, v121, s66, -v251
	v_fma_f32 v236, v122, s66, -v236
	v_fma_f32 v237, v123, s66, -v237
	v_fma_f32 v238, v124, s66, -v238
	v_fma_f32 v239, v125, s66, -v239
	v_fma_f32 v154, v126, s66, -v154
	v_fma_f32 v155, v127, s66, -v155
	v_fma_f32 v156, v128, s66, -v156
	v_fma_f32 v157, v129, s66, -v157
	ds_read_b64_tr_b16 v[122:123], v233 offset:5184
	ds_read_b64_tr_b16 v[126:127], v233 offset:5248
	ds_read_b64_tr_b16 v[114:115], v233 offset:5312
	ds_read_b64_tr_b16 v[152:153], v233 offset:7680
	ds_read_b64_tr_b16 v[124:125], v233 offset:7744
	ds_read_b64_tr_b16 v[128:129], v233 offset:7808
	ds_read_b64_tr_b16 v[116:117], v233 offset:7872
	ds_read_b128 v[118:121], v15 offset:192
	ds_read_b128 v[142:145], v15 offset:224
	s_waitcnt lgkmcnt(10)
	v_fma_f32 v245, v99, s66, -v245
	s_waitcnt lgkmcnt(9)
	s_waitcnt lgkmcnt(1)
	v_fma_f32 v244, v98, s66, -v244
	v_fma_f32 v246, v100, s66, -v246
	v_fma_f32 v247, v101, s66, -v247
	v_mfma_f32_32x32x16_bf16 v[66:81], v[130:133], v[18:21], v[66:81]
	v_max_f32_e32 v100, v241, v245
	v_fma_f32 v158, v102, s66, -v158
	v_fma_f32 v159, v103, s66, -v159
	v_fma_f32 v254, v108, s66, -v120
	v_max3_f32 v100, v240, v244, v100
	v_max_f32_e32 v101, v242, v246
	v_mfma_f32_32x32x16_bf16 v[34:49], v[150:153], v[10:13], v[34:49]
	v_max_f32_e32 v108, v243, v247
	v_fma_f32 v160, v104, s66, -v160
	v_fma_f32 v161, v105, s66, -v161
	v_max3_f32 v100, v100, v101, v108
	v_max_f32_e32 v101, v248, v158
	v_max_f32_e32 v108, v249, v159
	v_fma_f32 v252, v106, s66, -v118
	v_fma_f32 v253, v107, s66, -v119
	v_max3_f32 v100, v100, v101, v108
	v_max_f32_e32 v101, v250, v160
	v_max_f32_e32 v108, v251, v161
	s_waitcnt lgkmcnt(0)
	v_fma_f32 v225, v109, s66, -v121
	v_max3_f32 v100, v100, v101, v108
	v_max_f32_e32 v101, v236, v252
	v_max_f32_e32 v108, v237, v253
	v_fma_f32 v226, v110, s66, -v142
	v_fma_f32 v210, v111, s66, -v143
	v_max3_f32 v100, v100, v101, v108
	v_max_f32_e32 v101, v238, v254
	v_max_f32_e32 v108, v239, v225
	ds_read_b64_tr_b16 v[138:139], v233 offset:10240
	ds_read_b64_tr_b16 v[142:143], v233 offset:10304
	ds_read_b64_tr_b16 v[146:147], v233 offset:10368
	v_fma_f32 v211, v112, s66, -v144
	v_fma_f32 v212, v113, s66, -v145
	v_max3_f32 v100, v100, v101, v108
	v_max_f32_e32 v101, v154, v226
	v_max_f32_e32 v108, v155, v210
	ds_read_b64_tr_b16 v[118:119], v233 offset:10432
	ds_read_b64_tr_b16 v[140:141], v233 offset:12800
	ds_read_b64_tr_b16 v[144:145], v233 offset:12864
	ds_read_b64_tr_b16 v[148:149], v233 offset:12928
	ds_read_b64_tr_b16 v[120:121], v233 offset:12992
	v_max3_f32 v100, v100, v101, v108
	v_max_f32_e32 v101, v156, v211
	v_max_f32_e32 v108, v157, v212
	ds_read_b64_tr_b16 v[104:105], v233 offset:17920
	v_mfma_f32_32x32x16_bf16 v[66:81], v[126:129], v[10:13], v[66:81]
	v_max3_f32 v126, v100, v101, v108
	ds_bpermute_b32 v127, v31, v126
	ds_read_b64_tr_b16 v[102:103], v233 offset:15360
	ds_read_b64_tr_b16 v[106:107], v233 offset:15424
	ds_read_b64_tr_b16 v[110:111], v233 offset:15488
	ds_read_b64_tr_b16 v[98:99], v233 offset:15552
	ds_read_b64_tr_b16 v[108:109], v233 offset:17984
	ds_read_b64_tr_b16 v[112:113], v233 offset:18048
	ds_read_b64_tr_b16 v[100:101], v233 offset:18112
	v_add_u32_e32 v15, 0x100, v15
	s_waitcnt lgkmcnt(7)
	v_max_f32_e32 v126, v126, v127
	v_add_f32_e32 v126, v126, v234
	v_max_f32_e32 v127, v235, v126
	v_mfma_f32_32x32x16_bf16 v[34:49], v[138:141], v[6:9], v[34:49]
	v_cmp_neq_f32_e32 vcc, s34, v127
	s_nop 1
	v_cndmask_b32_e32 v126, 0, v127, vcc
	v_sub_f32_e32 v131, v235, v126
	v_sub_f32_e32 v126, v126, v234
	v_mov_b32_e32 v234, v127
	v_sub_f32_e32 v127, v240, v126
	v_exp_f32_e32 v127, v127
	v_mfma_f32_32x32x16_bf16 v[82:97], v[26:29], v[18:21], v[82:97]
	v_sub_f32_e32 v26, v246, v126
	v_exp_f32_e32 v133, v26
	v_sub_f32_e32 v26, v243, v126
	v_exp_f32_e32 v134, v26
	v_sub_f32_e32 v26, v247, v126
	v_exp_f32_e32 v135, v26
	v_sub_f32_e32 v28, v159, v126
	s_waitcnt lgkmcnt(6)
	v_mfma_f32_32x32x16_bf16 v[34:49], v[102:105], v[2:5], v[34:49]
	v_sub_f32_e32 v102, v244, v126
	v_exp_f32_e32 v128, v102
	v_sub_f32_e32 v102, v241, v126
	v_exp_f32_e32 v129, v102
	v_sub_f32_e32 v102, v245, v126
	v_exp_f32_e32 v130, v102
	v_add_f32_e32 v102, v128, v127
	v_mfma_f32_32x32x16_bf16 v[82:97], v[122:125], v[10:13], v[82:97]
	v_add_f32_e32 v102, 0, v102
	v_add_f32_e32 v103, v130, v129
	v_add_f32_e32 v102, v103, v102
	v_sub_f32_e32 v103, v242, v126
	v_exp_f32_e32 v132, v103
	v_add_f32_e32 v27, v135, v134
	v_exp_f32_e32 v28, v28
	v_mfma_f32_32x32x16_bf16 v[66:81], v[146:149], v[6:9], v[66:81]
	v_add_f32_e32 v26, v133, v132
	v_add_f32_e32 v26, v26, v102
	v_sub_f32_e32 v102, v250, v126
	v_exp_f32_e32 v103, v102
	v_sub_f32_e32 v102, v160, v126
	v_exp_f32_e32 v105, v102
	v_sub_f32_e32 v102, v251, v126
	v_mfma_f32_32x32x16_bf16 v[82:97], v[142:145], v[6:9], v[82:97]
	v_sub_f32_e32 v104, v161, v126
	v_exp_f32_e32 v102, v102
	v_exp_f32_e32 v104, v104
	s_waitcnt lgkmcnt(1)
; #define ATT_QK(KOFF, X0, X1) { X0 = zero16(); X1 = zero16(); _Pragma("unroll") for (int kk = 0; kk < 8; ++kk) { \
;         const bf16x8 f0 = *(const LAS bf16x8*)(lds + (KOFF) + kroff + 32 * kk), f1 = *(const LAS bf16x8*)(lds + (KOFF) + kroff + 32 * KSTR + 32 * kk); \
;         X0 = mfma32(f0, qf[kk], X0); X1 = mfma32(f1, qf[kk], X1); } }
; __device__ __forceinline__ void attn_item(LAS unsigned char* lds, const bf16_t* Z, bf16_t* Y, const float* logf, const float* ksum, const float* rel_bias,
;                                           const int moba, const int b, const int h, const int qt) {
;     ...
;     const float lut128 = moba ? lut[128] : 0.f;
;     const int t_int = moba ? ((qt > 0) ? 4 * qt - 2 : 0) : 4 * qt;
;     int vcur = 0, t = 0;
;     if (t_int > 0) {
;         bf16x8 pq[4];
;         { f32x16 x0, x1; ATT_STAGE(0, KB_SZ, 1) ATT_QK(0, x0, x1) ATT_SMFAST(0, x0, x1, pq) }
;         vcur = 1; __syncthreads();
;         for (t = 1; t < t_int; ++t) {
;             const int kc = (t & 1) * KB_SZ, kn = KB_SZ - kc;
;             const int vnx = (vcur == 2) ? 0 : vcur + 1, vpv = (vcur == 0) ? 2 : vcur - 1;
;             ATT_STAGE(t, kn, vnx)
;             f32x16 x0, x1;
;             ATT_QK(kc, x0, x1)
;             ATT_PVALL(pq, V_BASE + vpv * VB_SZ)
;             ATT_SMFAST(64 * t, x0, x1, pq)
;             vcur = vnx; __syncthreads();
;         }
;         { const int vpv = (vcur == 0) ? 2 : vcur - 1; ATT_PVALL(pq, V_BASE + vpv * VB_SZ) }
	v_mfma_f32_32x32x16_bf16 v[66:81], v[110:113], v[2:5], v[66:81]
	v_add_f32_e32 v110, v27, v26
	v_sub_f32_e32 v26, v248, v126
	v_exp_f32_e32 v27, v26
	v_sub_f32_e32 v26, v158, v126
	v_exp_f32_e32 v29, v26
	v_sub_f32_e32 v26, v249, v126
	v_exp_f32_e32 v26, v26
	v_mfma_f32_32x32x16_bf16 v[50:65], v[22:25], v[18:21], v[50:65]
	v_sub_f32_e32 v112, v225, v126
	v_exp_f32_e32 v112, v112
	v_sub_f32_e32 v18, v226, v126
	v_exp_f32_e32 v23, v18
	v_sub_f32_e32 v18, v155, v126
	v_mfma_f32_32x32x16_bf16 v[82:97], v[106:109], v[2:5], v[82:97]
	v_add_f32_e64 v106, v28, v26
	v_add_f32_e64 v107, v29, v27
	v_add_f32_e32 v107, v107, v110
	v_add_f32_e32 v108, v106, v107
	v_add_f32_e64 v106, v104, v102
	v_add_f32_e64 v107, v105, v103
	v_sub_f32_e32 v110, v238, v126
	v_add_f32_e32 v107, v107, v108
	v_mfma_f32_32x32x16_bf16 v[50:65], v[114:117], v[10:13], v[50:65]
	v_add_f32_e32 v124, v106, v107
	v_sub_f32_e32 v106, v236, v126
	v_exp_f32_e32 v107, v106
	v_sub_f32_e32 v106, v252, v126
	v_exp_f32_e32 v109, v106
	v_sub_f32_e32 v106, v237, v126
	v_sub_f32_e32 v108, v253, v126
	v_exp_f32_e32 v106, v106
	v_exp_f32_e32 v108, v108
	v_exp_f32_e32 v111, v110
	v_sub_f32_e32 v110, v254, v126
	v_exp_f32_e32 v113, v110
	v_sub_f32_e32 v110, v239, v126
	v_exp_f32_e32 v110, v110
	v_mfma_f32_32x32x16_bf16 v[50:65], v[118:121], v[6:9], v[50:65]
	v_add_f32_e64 v122, v108, v106
	v_add_f32_e64 v123, v109, v107
	v_sub_f32_e32 v10, v211, v126
	v_add_f32_e32 v123, v123, v124
	v_add_f32_e32 v124, v122, v123
	v_pk_add_f32 v[122:123], v[112:113], v[110:111]
	v_exp_f32_e32 v115, v10
	v_add_f32_e32 v123, v123, v124
	v_add_f32_e32 v124, v122, v123
	v_sub_f32_e32 v122, v154, v126
	v_exp_f32_e32 v123, v122
	v_exp_f32_e32 v122, v18
	v_sub_f32_e32 v18, v210, v126
	v_exp_f32_e32 v22, v18
	v_sub_f32_e32 v10, v157, v126
	v_sub_f32_e32 v18, v156, v126
	v_exp_f32_e32 v24, v10
	v_sub_f32_e32 v10, v212, v126
	s_waitcnt lgkmcnt(0)
	v_mfma_f32_32x32x16_bf16 v[50:65], v[98:101], v[2:5], v[50:65]
	v_exp_f32_e32 v25, v18
	v_exp_f32_e32 v114, v10
	v_pk_add_f32 v[6:7], v[22:23], v[122:123]
	v_exp_f32_e32 v116, v131
	v_add_f32_e32 v7, v7, v124
	v_add_f32_e32 v8, v6, v7
	v_pk_add_f32 v[6:7], v[114:115], v[24:25]
	v_pk_mul_f32 v[48:49], v[48:49], v[116:117] op_sel_hi:[1,0]
	v_add_f32_e32 v7, v7, v8
	v_add_f32_e32 v233, v6, v7
	v_fmac_f32_e32 v233, v33, v116
	v_pk_mul_f32 v[46:47], v[46:47], v[116:117] op_sel_hi:[1,0]
	v_pk_mul_f32 v[44:45], v[44:45], v[116:117] op_sel_hi:[1,0]
	v_pk_mul_f32 v[42:43], v[42:43], v[116:117] op_sel_hi:[1,0]
	v_pk_mul_f32 v[40:41], v[40:41], v[116:117] op_sel_hi:[1,0]
	v_pk_mul_f32 v[38:39], v[38:39], v[116:117] op_sel_hi:[1,0]
	v_pk_mul_f32 v[36:37], v[36:37], v[116:117] op_sel_hi:[1,0]
	v_pk_mul_f32 v[34:35], v[34:35], v[116:117] op_sel_hi:[1,0]
	v_pk_mul_f32 v[96:97], v[96:97], v[116:117] op_sel_hi:[1,0]
	v_pk_mul_f32 v[94:95], v[94:95], v[116:117] op_sel_hi:[1,0]
	v_pk_mul_f32 v[92:93], v[92:93], v[116:117] op_sel_hi:[1,0]
	v_pk_mul_f32 v[90:91], v[90:91], v[116:117] op_sel_hi:[1,0]
	v_pk_mul_f32 v[88:89], v[88:89], v[116:117] op_sel_hi:[1,0]
	v_pk_mul_f32 v[86:87], v[86:87], v[116:117] op_sel_hi:[1,0]
	v_pk_mul_f32 v[84:85], v[84:85], v[116:117] op_sel_hi:[1,0]
	v_pk_mul_f32 v[82:83], v[82:83], v[116:117] op_sel_hi:[1,0]
	v_pk_mul_f32 v[80:81], v[80:81], v[116:117] op_sel_hi:[1,0]
	v_pk_mul_f32 v[78:79], v[78:79], v[116:117] op_sel_hi:[1,0]
	v_pk_mul_f32 v[76:77], v[76:77], v[116:117] op_sel_hi:[1,0]
	v_pk_mul_f32 v[74:75], v[74:75], v[116:117] op_sel_hi:[1,0]
	v_pk_mul_f32 v[72:73], v[72:73], v[116:117] op_sel_hi:[1,0]
	v_pk_mul_f32 v[70:71], v[70:71], v[116:117] op_sel_hi:[1,0]
	v_pk_mul_f32 v[68:69], v[68:69], v[116:117] op_sel_hi:[1,0]
	v_pk_mul_f32 v[66:67], v[66:67], v[116:117] op_sel_hi:[1,0]
	v_pk_mul_f32 v[64:65], v[64:65], v[116:117] op_sel_hi:[1,0]
	v_pk_mul_f32 v[62:63], v[62:63], v[116:117] op_sel_hi:[1,0]
	v_pk_mul_f32 v[60:61], v[60:61], v[116:117] op_sel_hi:[1,0]
	v_pk_mul_f32 v[58:59], v[58:59], v[116:117] op_sel_hi:[1,0]
	v_pk_mul_f32 v[56:57], v[56:57], v[116:117] op_sel_hi:[1,0]
	v_pk_mul_f32 v[54:55], v[54:55], v[116:117] op_sel_hi:[1,0]
	v_pk_mul_f32 v[52:53], v[52:53], v[116:117] op_sel_hi:[1,0]
	v_pk_mul_f32 v[50:51], v[50:51], v[116:117] op_sel_hi:[1,0]
	v_cvt_pk_bf16_f32 v18, v127, v129
	v_cvt_pk_bf16_f32 v19, v132, v134
	v_cvt_pk_bf16_f32 v20, v27, v26
	v_cvt_pk_bf16_f32 v21, v103, v102
	v_cvt_pk_bf16_f32 v10, v107, v106
	v_cvt_pk_bf16_f32 v11, v111, v110
	v_cvt_pk_bf16_f32 v12, v123, v122
	v_cvt_pk_bf16_f32 v13, v25, v24
	v_cvt_pk_bf16_f32 v6, v128, v130
	v_cvt_pk_bf16_f32 v7, v133, v135
	v_cvt_pk_bf16_f32 v8, v29, v28
	v_cvt_pk_bf16_f32 v9, v105, v104
	v_cvt_pk_bf16_f32 v2, v109, v108
	v_cvt_pk_bf16_f32 v3, v113, v112
	v_cvt_pk_bf16_f32 v4, v23, v22
	v_cvt_pk_bf16_f32 v5, v115, v114
	s_barrier
	s_cbranch_scc0 .LBB0_167
	v_mov_b32_e32 v235, v234
	v_mov_b32_e32 v33, v233
	s_mov_b32 s9, s37
	s_mov_b32 s14, s8
	s_branch .LBB0_159

; __device__ __forceinline__ void pool_item(LAS unsigned char* lds, const bf16_t* Z, bf16_t* Y, const bf16_t* PW, const float* pscale, const int tile, const int g) {
;     ...
;       if (g == 0) { POOL_ROWS(2) } else if (g == 1) { POOL_ROWS(4) } else if (g == 2) { POOL_ROWS(8) } else { POOL_ROWS(16) }
.LBB0_234:
	v_add_u32_e32 v9, s6, v6
	v_add_u32_e32 v12, 0x11000, v9
	ds_read_b32 v20, v12
	ds_read_b32 v21, v12 offset:272
	ds_read_b32 v22, v12 offset:544
	ds_read_b32 v23, v12 offset:816
	ds_read_b32 v24, v12 offset:1088
	ds_read_b32 v25, v12 offset:1360
	ds_read_b32 v26, v12 offset:1632
	ds_read_b32 v27, v12 offset:1904
	ds_read_b32 v28, v12 offset:2176
	ds_read_b32 v29, v12 offset:2448
	ds_read_b32 v30, v12 offset:2720
	ds_read_b32 v31, v12 offset:2992
	ds_read_b32 v32, v12 offset:3264
	ds_read_b32 v33, v12 offset:3536
	ds_read_b32 v34, v12 offset:3808
	ds_read_b32 v35, v12 offset:4080
	v_min_u32_e32 v1, 15, v7
	v_add_u32_e32 v1, 1, v1
	v_cvt_f32_ubyte0_e32 v1, v1
	s_addk_i32 s6, 0x110
	s_waitcnt lgkmcnt(0)
	v_lshlrev_b32_e32 v2, 16, v20
	v_and_b32_e32 v3, 0xffff0000, v20
	v_pk_add_f32 v[2:3], v[2:3], 0 op_sel_hi:[1,0]
	v_lshlrev_b32_e32 v10, 16, v21
	v_and_b32_e32 v11, 0xffff0000, v21
	v_add_f32_e32 v2, v2, v10
	v_add_f32_e32 v3, v3, v11
	v_lshlrev_b32_e32 v10, 16, v22
	v_and_b32_e32 v11, 0xffff0000, v22
	v_add_f32_e32 v2, v2, v10
	v_add_f32_e32 v3, v3, v11
	v_lshlrev_b32_e32 v10, 16, v23
	v_and_b32_e32 v11, 0xffff0000, v23
	v_add_f32_e32 v2, v2, v10
	v_add_f32_e32 v3, v3, v11
	v_lshlrev_b32_e32 v10, 16, v24
	v_and_b32_e32 v11, 0xffff0000, v24
	v_add_f32_e32 v2, v2, v10
	v_add_f32_e32 v3, v3, v11
	v_lshlrev_b32_e32 v10, 16, v25
	v_and_b32_e32 v11, 0xffff0000, v25
	v_add_f32_e32 v2, v2, v10
	v_add_f32_e32 v3, v3, v11
	v_lshlrev_b32_e32 v10, 16, v26
	v_and_b32_e32 v11, 0xffff0000, v26
	v_add_f32_e32 v2, v2, v10
	v_add_f32_e32 v3, v3, v11
	v_lshlrev_b32_e32 v10, 16, v27
	v_and_b32_e32 v11, 0xffff0000, v27
	v_add_f32_e32 v2, v2, v10
	v_add_f32_e32 v3, v3, v11
	v_lshlrev_b32_e32 v10, 16, v28
	v_and_b32_e32 v11, 0xffff0000, v28
	v_add_f32_e32 v2, v2, v10
	v_add_f32_e32 v3, v3, v11
	v_lshlrev_b32_e32 v10, 16, v29
	v_and_b32_e32 v11, 0xffff0000, v29
	v_add_f32_e32 v2, v2, v10
	v_add_f32_e32 v3, v3, v11
	v_lshlrev_b32_e32 v10, 16, v30
	v_and_b32_e32 v11, 0xffff0000, v30
	v_add_f32_e32 v2, v2, v10
	v_add_f32_e32 v3, v3, v11
	v_lshlrev_b32_e32 v10, 16, v31
	v_and_b32_e32 v11, 0xffff0000, v31
	v_add_f32_e32 v2, v2, v10
	v_add_f32_e32 v3, v3, v11
	v_lshlrev_b32_e32 v10, 16, v32
	v_and_b32_e32 v11, 0xffff0000, v32
	v_add_f32_e32 v2, v2, v10
	v_add_f32_e32 v3, v3, v11
	v_lshlrev_b32_e32 v10, 16, v33
	v_and_b32_e32 v11, 0xffff0000, v33
	v_add_f32_e32 v2, v2, v10
	v_add_f32_e32 v3, v3, v11
	v_lshlrev_b32_e32 v10, 16, v34
	v_and_b32_e32 v11, 0xffff0000, v34
	v_add_f32_e32 v2, v2, v10
	v_add_f32_e32 v3, v3, v11
	v_and_b32_e32 v11, 0xffff0000, v35
	v_lshlrev_b32_e32 v10, 16, v35
	v_add_f32_e32 v2, v2, v10
	v_div_scale_f32 v12, s[4:5], v1, v1, v2
	v_rcp_f32_e32 v13, v12
	v_add_f32_e32 v3, v3, v11
	v_add_u32_e32 v7, 1, v7
	s_cmpk_lg_i32 s6, 0x2200
	v_fma_f32 v14, -v12, v13, 1.0
	v_fmac_f32_e32 v13, v14, v13
	v_div_scale_f32 v14, vcc, v2, v1, v2
	v_mul_f32_e32 v18, v14, v13
	v_fma_f32 v19, -v12, v18, v14
	v_fmac_f32_e32 v18, v19, v13
	v_fma_f32 v12, -v12, v18, v14
	v_div_fmas_f32 v12, v12, v13, v18
	v_div_fixup_f32 v2, v12, v1, v2
	v_sub_f32_e32 v2, v2, v10
	v_div_scale_f32 v10, s[4:5], v1, v1, v3
	v_rcp_f32_e32 v12, v10
	s_nop 0
	v_fma_f32 v13, -v10, v12, 1.0
	v_fmac_f32_e32 v12, v13, v12
	v_div_scale_f32 v13, vcc, v3, v1, v3
	v_mul_f32_e32 v14, v13, v12
	v_fma_f32 v18, -v10, v14, v13
	v_fmac_f32_e32 v14, v18, v12
	v_fma_f32 v10, -v10, v14, v13
	v_div_fmas_f32 v10, v10, v12, v14
	v_div_fixup_f32 v1, v10, v1, v3
	v_sub_f32_e32 v1, v1, v11
	v_cvt_pk_bf16_f32 v1, v2, v1
	ds_write_b32 v9, v1
	s_cbranch_scc1 .LBB0_234

; __device__ __forceinline__ void pool_item(LAS unsigned char* lds, const bf16_t* Z, bf16_t* Y, const bf16_t* PW, const float* pscale, const int tile, const int g) {
;     ...
;       if (g == 0) { POOL_ROWS(2) } else if (g == 1) { POOL_ROWS(4) } else if (g == 2) { POOL_ROWS(8) } else { POOL_ROWS(16) }
.LBB0_268:
	v_add_u32_e32 v9, s6, v6
	v_add_u32_e32 v12, 0x11880, v9
	ds_read_b32 v20, v12
	ds_read_b32 v21, v12 offset:272
	ds_read_b32 v22, v12 offset:544
	ds_read_b32 v23, v12 offset:816
	ds_read_b32 v24, v12 offset:1088
	ds_read_b32 v25, v12 offset:1360
	ds_read_b32 v26, v12 offset:1632
	ds_read_b32 v27, v12 offset:1904
	v_min_u32_e32 v1, 7, v7
	v_add_u32_e32 v1, 1, v1
	v_cvt_f32_ubyte0_e32 v1, v1
	s_addk_i32 s6, 0x110
	s_waitcnt lgkmcnt(0)
	v_lshlrev_b32_e32 v3, 16, v20
	v_and_b32_e32 v2, 0xffff0000, v20
	v_pk_add_f32 v[2:3], v[2:3], 0 op_sel_hi:[1,0]
	v_lshlrev_b32_e32 v11, 16, v21
	v_and_b32_e32 v10, 0xffff0000, v21
	v_add_f32_e32 v2, v2, v10
	v_add_f32_e32 v3, v3, v11
	v_lshlrev_b32_e32 v11, 16, v22
	v_and_b32_e32 v10, 0xffff0000, v22
	v_add_f32_e32 v2, v2, v10
	v_add_f32_e32 v3, v3, v11
	v_lshlrev_b32_e32 v11, 16, v23
	v_and_b32_e32 v10, 0xffff0000, v23
	v_add_f32_e32 v2, v2, v10
	v_add_f32_e32 v3, v3, v11
	v_lshlrev_b32_e32 v11, 16, v24
	v_and_b32_e32 v10, 0xffff0000, v24
	v_add_f32_e32 v2, v2, v10
	v_add_f32_e32 v3, v3, v11
	v_lshlrev_b32_e32 v11, 16, v25
	v_and_b32_e32 v10, 0xffff0000, v25
	v_add_f32_e32 v2, v2, v10
	v_add_f32_e32 v3, v3, v11
	v_lshlrev_b32_e32 v11, 16, v26
	v_and_b32_e32 v10, 0xffff0000, v26
	v_add_f32_e32 v2, v2, v10
	v_add_f32_e32 v3, v3, v11
	v_and_b32_e32 v11, 0xffff0000, v27
	v_lshlrev_b32_e32 v10, 16, v27
	v_add_f32_e32 v3, v3, v10
	v_div_scale_f32 v12, s[4:5], v1, v1, v3
	v_rcp_f32_e32 v13, v12
	v_add_f32_e32 v2, v2, v11
	v_add_u32_e32 v7, 1, v7
	s_cmpk_eq_i32 s6, 0x2200
	v_fma_f32 v14, -v12, v13, 1.0
	v_fmac_f32_e32 v13, v14, v13
	v_div_scale_f32 v14, vcc, v3, v1, v3
	v_mul_f32_e32 v18, v14, v13
	v_fma_f32 v19, -v12, v18, v14
	v_fmac_f32_e32 v18, v19, v13
	v_fma_f32 v12, -v12, v18, v14
	v_div_fmas_f32 v12, v12, v13, v18
	v_div_fixup_f32 v3, v12, v1, v3
	v_sub_f32_e32 v3, v3, v10
	v_div_scale_f32 v10, s[4:5], v1, v1, v2
	v_rcp_f32_e32 v12, v10
	s_nop 0
	v_fma_f32 v13, -v10, v12, 1.0
	v_fmac_f32_e32 v12, v13, v12
	v_div_scale_f32 v13, vcc, v2, v1, v2
	v_mul_f32_e32 v14, v13, v12
	v_fma_f32 v18, -v10, v14, v13
	v_fmac_f32_e32 v14, v18, v12
	v_fma_f32 v10, -v10, v14, v13
	v_div_fmas_f32 v10, v10, v12, v14
	v_div_fixup_f32 v1, v10, v1, v2
	v_sub_f32_e32 v1, v1, v11
	v_cvt_pk_bf16_f32 v1, v3, v1
	ds_write_b32 v9, v1
	s_cbranch_scc0 .LBB0_268
